# final RMSNorm: read-once residual loads marked nt (cache policy)
# speedup vs baseline: 1.0077x; 1.0077x over previous
; __global__ void __launch_bounds__(NTHREADS, 2) mk_fwd(Args a) {
;     ...
;     {
;         const float* ss6 = ssp + (size_t)6 * SSP_STRIDE;
;         const bool local = bst[3] != 0u; const int xq = (int)bar.x, rank = (int)bst[2], nl = G / 8;
;         const int fn_first = local ? xq * SEQ + rank * NWAVES : vcu * NWAVES, fn_stride = (local ? nl : G) * NWAVES, fn_end = local ? (xq + 1) * SEQ : M;
;         f32x4 gv[2][2];
; #pragma unroll
;         for (int p = 0; p < 2; ++p) { gv[p][0] = *(const f32x4*)(P.final_g + p * 512 + lane * 8); gv[p][1] = *(const f32x4*)(P.final_g + p * 512 + lane * 8 + 4); }
;         for (int m = fn_first + wave; m < fn_end; m += fn_stride) {
;             const float rs = row_rstd(ss6, m);
; #pragma unroll
;             for (int p = 0; p < 2; ++p) {
;                 const u32x4 w = *(const u32x4*)(xb + (size_t)m * D + p * 512 + lane * 8);
;                 const f32x4 v0 = (f32x4){__uint_as_float(w.x << 16), __uint_as_float(w.x & 0xffff0000u), __uint_as_float(w.y << 16), __uint_as_float(w.y & 0xffff0000u)};
;                 const f32x4 v1 = (f32x4){__uint_as_float(w.z << 16), __uint_as_float(w.z & 0xffff0000u), __uint_as_float(w.w << 16), __uint_as_float(w.w & 0xffff0000u)};
;                 float* o = P.out + (size_t)m * D + p * 512 + lane * 8;
;                 __builtin_nontemporal_store(v0 * rs * gv[p][0], (f32x4*)o); __builtin_nontemporal_store(v1 * rs * gv[p][1], (f32x4*)(o + 4));
;             }
;         }
.LBB0_319:
	s_add_i32 s0, 0, 0x23ffc
	v_mov_b32_e32 v0, s0
	s_add_i32 s0, 0, 0x23ff8
	v_mov_b32_e32 v1, s0
	ds_read_b32 v0, v0
	ds_read_b32 v1, v1
	v_readlane_b32 s1, v253, 47
	s_add_i32 s2, s1, 0x1000
	s_waitcnt lgkmcnt(0)
	v_readfirstlane_b32 s0, v1
	s_lshl_b32 s0, s0, 3
	s_add_i32 s3, s0, s1
	v_readfirstlane_b32 s0, v0
	s_cmp_eq_u32 s0, 0
	s_cselect_b64 vcc, -1, 0
	s_and_b64 s[0:1], vcc, exec
	v_readlane_b32 s0, v253, 41
	s_cselect_b32 s1, s0, s3
	s_cselect_b32 s6, 0x8000, s2
	v_readlane_b32 s2, v255, 25
	s_add_i32 s0, s1, s2
	s_cmp_lt_i32 s0, s6
	s_cbranch_scc0 .LBB0_322
	v_readlane_b32 s8, v253, 2
	v_lshlrev_b32_e32 v20, 5, v232
	v_readlane_b32 s12, v253, 6
	v_readlane_b32 s13, v253, 7
	s_nop 4
	global_load_dwordx4 v[0:3], v20, s[12:13] offset:16
	global_load_dwordx4 v[4:7], v20, s[12:13]
	global_load_dwordx4 v[8:11], v20, s[12:13] offset:2064
	global_load_dwordx4 v[12:15], v20, s[12:13] offset:2048
	s_mov_b64 s[4:5], s[12:13]
	v_readlane_b32 s14, v253, 8
	v_readlane_b32 s15, v253, 9
	v_readlane_b32 s16, v253, 10
	v_readlane_b32 s17, v253, 11
	v_readlane_b32 s18, v253, 12
	v_readlane_b32 s19, v253, 13
	v_readlane_b32 s20, v253, 14
	v_readlane_b32 s21, v253, 15
	v_readlane_b32 s22, v253, 16
	v_readlane_b32 s23, v253, 17
	s_ashr_i32 s3, s1, 31
	s_ashr_i32 s4, s2, 31
	s_add_u32 s2, s1, s2
	v_readlane_b32 s12, v253, 18
	v_readlane_b32 s9, v253, 3
	s_addc_u32 s3, s3, s4
	v_readlane_b32 s14, v253, 20
	v_readlane_b32 s15, v253, 21
	v_readlane_b32 s26, v253, 32
	v_readlane_b32 s27, v253, 33
	v_mov_b32_e32 v16, s90
	s_lshl_b64 s[4:5], s[2:3], 6
	s_lshl_b64 s[8:9], s[2:3], 12
	s_mov_b64 s[14:15], s[26:27]
	v_cndmask_b32_e32 v16, v233, v16, vcc
	s_add_u32 s8, s14, s8
	v_lshlrev_b32_e32 v16, 3, v16
	v_mov_b32_e32 v21, 0
	s_addc_u32 s9, s15, s9
	v_ashrrev_i32_e32 v17, 31, v16
	v_lshl_add_u64 v[20:21], s[8:9], 0, v[20:21]
	s_mov_b64 s[8:9], 0x810
	s_lshl_b64 s[2:3], s[2:3], 11
	v_lshlrev_b64 v[18:19], 6, v[16:17]
	v_lshl_add_u64 v[20:21], v[20:21], 0, s[8:9]
	v_lshlrev_b64 v[22:23], 12, v[16:17]
	v_lshl_or_b32 v24, v232, 4, s2
	v_mov_b32_e32 v25, s3
	v_lshlrev_b64 v[26:27], 11, v[16:17]
	s_mov_b64 s[2:3], 0
	v_mov_b64_e32 v[28:29], s[4:5]
	v_mov_b32_e32 v17, s0
	s_mov_b64 s[4:5], 0xc00000
	v_mov_b32_e32 v30, 0x358637bd
	s_mov_b32 s7, 0x800000
	s_mov_b32 s8, 0x6200000
	v_readlane_b32 s10, v253, 4
	v_readlane_b32 s11, v253, 5
	v_readlane_b32 s13, v253, 19
	v_readlane_b32 s16, v253, 22
	v_readlane_b32 s17, v253, 23
	v_readlane_b32 s18, v253, 24
	v_readlane_b32 s19, v253, 25
	v_readlane_b32 s20, v253, 26
	v_readlane_b32 s21, v253, 27
	v_readlane_b32 s22, v253, 28
	v_readlane_b32 s23, v253, 29
	v_readlane_b32 s24, v253, 30
	v_readlane_b32 s25, v253, 31
	s_mov_b32 s9, 0
	v_lshl_add_u64 v[52:53], s[88:89], 0, v[28:29]
	v_lshl_add_u64 v[56:57], s[88:89], 0, v[24:25]
	v_lshl_add_u64 v[52:53], v[52:53], 0, s[4:5]
	v_lshl_add_u64 v[56:57], v[56:57], 0, s[8:9]
	global_load_dwordx4 v[32:35], v[52:53], off offset:32
	global_load_dwordx4 v[36:39], v[52:53], off offset:16
	global_load_dwordx4 v[40:43], v[52:53], off
	global_load_dwordx4 v[44:47], v[52:53], off offset:48
	global_load_dwordx4 v[48:51], v[56:57], off nt
	global_load_dwordx4 v[60:63], v[56:57], off offset:1024 nt
	s_waitcnt vmcnt(0)
.Lmy_fn_loop:
	v_pk_add_f32 v[38:39], v[42:43], v[38:39]
	v_pk_add_f32 v[36:37], v[40:41], v[36:37]
	v_pk_add_f32 v[34:35], v[34:35], v[46:47]
	v_pk_add_f32 v[32:33], v[32:33], v[44:45]
	v_pk_add_f32 v[34:35], v[38:39], v[34:35]
	v_pk_add_f32 v[32:33], v[36:37], v[32:33]
	v_lshlrev_b32_e32 v64, 16, v48
	v_pk_mov_b32 v[36:37], v[32:33], v[34:35] op_sel:[1,0]
	v_mov_b32_e32 v33, v35
	v_pk_add_f32 v[32:33], v[36:37], v[32:33]
	v_and_b32_e32 v65, 0xffff0000, v48
	v_add_f32_e32 v31, v32, v33
	v_fmamk_f32 v31, v31, 0x3a800000, v30
	v_mul_f32_e32 v32, 0x4b800000, v31
	v_cmp_gt_f32_e32 vcc, s7, v31
	v_lshlrev_b32_e32 v66, 16, v49
	v_and_b32_e32 v67, 0xffff0000, v49
	v_cndmask_b32_e32 v31, v31, v32, vcc
	v_rsq_f32_e32 v31, v31
	v_lshlrev_b32_e32 v68, 16, v50
	v_and_b32_e32 v69, 0xffff0000, v50
	v_lshlrev_b32_e32 v70, 16, v51
	v_mul_f32_e32 v32, 0x45800000, v31
	v_cndmask_b32_e32 v58, v31, v32, vcc
	v_and_b32_e32 v71, 0xffff0000, v51
	v_lshlrev_b32_e32 v72, 16, v60
	v_and_b32_e32 v73, 0xffff0000, v60
	v_lshlrev_b32_e32 v74, 16, v61
	v_and_b32_e32 v75, 0xffff0000, v61
	v_lshlrev_b32_e32 v76, 16, v62
	v_and_b32_e32 v77, 0xffff0000, v62
	v_lshlrev_b32_e32 v78, 16, v63
	v_and_b32_e32 v79, 0xffff0000, v63
	v_mov_b32_e32 v80, v20
	v_mov_b32_e32 v81, v21
	v_add_u32_e32 v17, v17, v16
	v_lshl_add_u64 v[28:29], v[28:29], 0, v[18:19]
	v_lshl_add_u64 v[24:25], v[24:25], 0, v[26:27]
	v_lshl_add_u64 v[20:21], v[20:21], 0, v[22:23]
	v_cmp_gt_i32_e32 vcc, s6, v17
	s_cbranch_vccz .Lmy_fn_nonext
	v_lshl_add_u64 v[52:53], s[88:89], 0, v[28:29]
	v_lshl_add_u64 v[56:57], s[88:89], 0, v[24:25]
	v_lshl_add_u64 v[52:53], v[52:53], 0, s[4:5]
	v_lshl_add_u64 v[56:57], v[56:57], 0, s[8:9]
	global_load_dwordx4 v[32:35], v[52:53], off offset:32
	global_load_dwordx4 v[36:39], v[52:53], off offset:16
	global_load_dwordx4 v[40:43], v[52:53], off
	global_load_dwordx4 v[44:47], v[52:53], off offset:48
	global_load_dwordx4 v[48:51], v[56:57], off nt
	global_load_dwordx4 v[60:63], v[56:57], off offset:1024 nt
